# rwkv_scan compute waves: one-step lookahead of the rank-1 coefficient (pd_(s+1) = X_(s+1) + pd_s*c_(s+1)) so the 16-lane reduction overlaps the state update; f32, exact algebra
# speedup vs baseline: 1.0089x; 1.0082x over previous
.LBB0_892:
	s_mul_i32 s11, s7, 0x6000
	s_add_i32 s11, s11, 0
	v_lshl_add_u32 v11, v7, 2, s11
	v_lshl_add_u32 v12, v4, 2, s11
	ds_read_b128 v[60:63], v11 offset:512
	ds_read_b128 v[64:67], v11 offset:256
	ds_read_b32 v68, v12 offset:1280
	ds_read_b128 v[72:75], v11
	ds_read_b128 v[76:79], v11 offset:768
	ds_read_b128 v[80:83], v11 offset:1024
	ds_read_b128 v[84:87], v11 offset:2048
	ds_read_b128 v[88:91], v11 offset:1792
	ds_read_b32 v92, v12 offset:2816
	ds_read_b128 v[96:99], v11 offset:1536
	ds_read_b128 v[100:103], v11 offset:2304
	ds_read_b128 v[104:107], v11 offset:2560
	s_and_b32 s11, s6, 0x1000
	v_lshl_add_u32 v10, s11, 2, v9
	s_waitcnt lgkmcnt(3)
	ds_read_b128 v[108:111], v11 offset:3584
	ds_read_b128 v[112:115], v11 offset:3328
	ds_read_b32 v116, v12 offset:4352
	ds_read_b128 v[120:123], v11 offset:3072
	ds_read_b128 v[124:127], v11 offset:3840
	ds_read_b128 v[128:131], v11 offset:4096
	v_mul_f32_e32 v30, v5, v68
	v_pk_mul_f32 v[18:19], v[64:65], v[30:31] op_sel_hi:[1,0]
	v_pk_mul_f32 v[20:21], v[66:67], v[30:31] op_sel_hi:[1,0]
	v_pk_mul_f32 v[22:23], v[0:1], v[60:61]
	v_pk_fma_f32 v[22:23], v[2:3], v[62:63], v[22:23]
	v_add_f32_e32 v26, v22, v23
	v_pk_fma_f32 v[14:15], v[0:1], v[72:73], v[18:19]
	v_pk_fma_f32 v[16:17], v[2:3], v[74:75], v[20:21]
	v_add_f32_dpp v26, v26, v26 quad_perm:[1,0,3,2] row_mask:0xf bank_mask:0xf bound_ctrl:1
	s_nop 1
	v_add_f32_dpp v26, v26, v26 quad_perm:[2,3,0,1] row_mask:0xf bank_mask:0xf bound_ctrl:1
	s_nop 1
	v_add_f32_dpp v26, v26, v26 row_half_mirror row_mask:0xf bank_mask:0xf bound_ctrl:1
	s_nop 1
	v_add_f32_dpp v28, v26, v26 row_mirror row_mask:0xf bank_mask:0xf bound_ctrl:1
	v_pk_fma_f32 v[40:41], v[76:77], v[28:29], v[14:15] op_sel_hi:[1,0,1]
	v_pk_fma_f32 v[42:43], v[78:79], v[28:29], v[16:17] op_sel_hi:[1,0,1]
	v_pk_mul_f32 v[22:23], v[14:15], v[84:85]
	v_pk_mul_f32 v[24:25], v[76:77], v[84:85]
	v_pk_fma_f32 v[22:23], v[16:17], v[86:87], v[22:23]
	v_pk_fma_f32 v[24:25], v[78:79], v[86:87], v[24:25]
	v_add_f32_e32 v26, v22, v23
	v_add_f32_e32 v27, v24, v25
	s_nop 0
	v_add_f32_dpp v26, v26, v26 quad_perm:[1,0,3,2] row_mask:0xf bank_mask:0xf bound_ctrl:1
	v_add_f32_dpp v27, v27, v27 quad_perm:[1,0,3,2] row_mask:0xf bank_mask:0xf bound_ctrl:1
	v_mul_f32_e32 v30, v5, v92
	v_pk_mul_f32 v[18:19], v[88:89], v[30:31] op_sel_hi:[1,0]
	v_add_f32_dpp v26, v26, v26 quad_perm:[2,3,0,1] row_mask:0xf bank_mask:0xf bound_ctrl:1
	v_add_f32_dpp v27, v27, v27 quad_perm:[2,3,0,1] row_mask:0xf bank_mask:0xf bound_ctrl:1
	v_pk_mul_f32 v[20:21], v[90:91], v[30:31] op_sel_hi:[1,0]
	v_add_f32_dpp v26, v26, v26 row_half_mirror row_mask:0xf bank_mask:0xf bound_ctrl:1
	v_add_f32_dpp v27, v27, v27 row_half_mirror row_mask:0xf bank_mask:0xf bound_ctrl:1
	s_nop 0
	v_add_f32_dpp v35, v26, v26 row_mirror row_mask:0xf bank_mask:0xf bound_ctrl:1
	v_add_f32_dpp v36, v27, v27 row_mirror row_mask:0xf bank_mask:0xf bound_ctrl:1
	s_waitcnt lgkmcnt(3)
	ds_read_b128 v[132:135], v11 offset:5120
	ds_read_b128 v[136:139], v11 offset:4864
	ds_read_b32 v140, v12 offset:5888
	ds_read_b128 v[144:147], v11 offset:4608
	ds_read_b128 v[148:151], v11 offset:5376
	ds_read_b128 v[152:155], v11 offset:5632
	v_pk_fma_f32 v[14:15], v[40:41], v[96:97], v[18:19]
	v_pk_fma_f32 v[16:17], v[42:43], v[98:99], v[20:21]
	v_fma_f32 v28, v28, v36, v35
	v_pk_fma_f32 v[0:1], v[100:101], v[28:29], v[14:15] op_sel_hi:[1,0,1]
	v_pk_fma_f32 v[2:3], v[102:103], v[28:29], v[16:17] op_sel_hi:[1,0,1]
	v_pk_mul_f32 v[22:23], v[14:15], v[108:109]
	v_pk_mul_f32 v[24:25], v[100:101], v[108:109]
	v_pk_fma_f32 v[22:23], v[16:17], v[110:111], v[22:23]
	v_pk_fma_f32 v[24:25], v[102:103], v[110:111], v[24:25]
	v_add_f32_e32 v26, v22, v23
	v_add_f32_e32 v27, v24, v25
	s_nop 0
	v_add_f32_dpp v26, v26, v26 quad_perm:[1,0,3,2] row_mask:0xf bank_mask:0xf bound_ctrl:1
	v_add_f32_dpp v27, v27, v27 quad_perm:[1,0,3,2] row_mask:0xf bank_mask:0xf bound_ctrl:1
	v_pk_mul_f32 v[32:33], v[40:41], v[80:81]
	v_pk_fma_f32 v[32:33], v[42:43], v[82:83], v[32:33]
	v_add_f32_dpp v26, v26, v26 quad_perm:[2,3,0,1] row_mask:0xf bank_mask:0xf bound_ctrl:1
	v_add_f32_dpp v27, v27, v27 quad_perm:[2,3,0,1] row_mask:0xf bank_mask:0xf bound_ctrl:1
	v_add_f32_e32 v32, v32, v33
	ds_write_b32 v10, v32
	v_add_f32_dpp v26, v26, v26 row_half_mirror row_mask:0xf bank_mask:0xf bound_ctrl:1
	v_add_f32_dpp v27, v27, v27 row_half_mirror row_mask:0xf bank_mask:0xf bound_ctrl:1
	v_mul_f32_e32 v30, v5, v116
	v_pk_mul_f32 v[18:19], v[112:113], v[30:31] op_sel_hi:[1,0]
	v_add_f32_dpp v35, v26, v26 row_mirror row_mask:0xf bank_mask:0xf bound_ctrl:1
	v_add_f32_dpp v36, v27, v27 row_mirror row_mask:0xf bank_mask:0xf bound_ctrl:1
	v_pk_mul_f32 v[20:21], v[114:115], v[30:31] op_sel_hi:[1,0]
	s_waitcnt lgkmcnt(4)
	ds_read_b128 v[60:63], v11 offset:6656
	ds_read_b128 v[64:67], v11 offset:6400
	ds_read_b32 v68, v12 offset:7424
	ds_read_b128 v[72:75], v11 offset:6144
	ds_read_b128 v[76:79], v11 offset:6912
	ds_read_b128 v[80:83], v11 offset:7168
	v_pk_fma_f32 v[14:15], v[0:1], v[120:121], v[18:19]
	v_pk_fma_f32 v[16:17], v[2:3], v[122:123], v[20:21]
	v_fma_f32 v28, v28, v36, v35
	v_pk_fma_f32 v[40:41], v[124:125], v[28:29], v[14:15] op_sel_hi:[1,0,1]
	v_pk_fma_f32 v[42:43], v[126:127], v[28:29], v[16:17] op_sel_hi:[1,0,1]
	v_pk_mul_f32 v[22:23], v[14:15], v[132:133]
	v_pk_mul_f32 v[24:25], v[124:125], v[132:133]
	v_pk_fma_f32 v[22:23], v[16:17], v[134:135], v[22:23]
	v_pk_fma_f32 v[24:25], v[126:127], v[134:135], v[24:25]
	v_add_f32_e32 v26, v22, v23
	v_add_f32_e32 v27, v24, v25
	s_nop 0
	v_add_f32_dpp v26, v26, v26 quad_perm:[1,0,3,2] row_mask:0xf bank_mask:0xf bound_ctrl:1
	v_add_f32_dpp v27, v27, v27 quad_perm:[1,0,3,2] row_mask:0xf bank_mask:0xf bound_ctrl:1
	v_pk_mul_f32 v[32:33], v[0:1], v[104:105]
	v_pk_fma_f32 v[32:33], v[2:3], v[106:107], v[32:33]
	v_add_f32_dpp v26, v26, v26 quad_perm:[2,3,0,1] row_mask:0xf bank_mask:0xf bound_ctrl:1
	v_add_f32_dpp v27, v27, v27 quad_perm:[2,3,0,1] row_mask:0xf bank_mask:0xf bound_ctrl:1
	v_add_f32_e32 v32, v32, v33
	ds_write_b32 v10, v32 offset:1024
	v_add_f32_dpp v26, v26, v26 row_half_mirror row_mask:0xf bank_mask:0xf bound_ctrl:1
	v_add_f32_dpp v27, v27, v27 row_half_mirror row_mask:0xf bank_mask:0xf bound_ctrl:1
	v_mul_f32_e32 v30, v5, v140
	v_pk_mul_f32 v[18:19], v[136:137], v[30:31] op_sel_hi:[1,0]
	v_add_f32_dpp v35, v26, v26 row_mirror row_mask:0xf bank_mask:0xf bound_ctrl:1
	v_add_f32_dpp v36, v27, v27 row_mirror row_mask:0xf bank_mask:0xf bound_ctrl:1
	v_pk_mul_f32 v[20:21], v[138:139], v[30:31] op_sel_hi:[1,0]
	s_waitcnt lgkmcnt(4)
	ds_read_b128 v[84:87], v11 offset:8192
	ds_read_b128 v[88:91], v11 offset:7936
	ds_read_b32 v92, v12 offset:8960
	ds_read_b128 v[96:99], v11 offset:7680
	ds_read_b128 v[100:103], v11 offset:8448
	ds_read_b128 v[104:107], v11 offset:8704
	v_pk_fma_f32 v[14:15], v[40:41], v[144:145], v[18:19]
	v_pk_fma_f32 v[16:17], v[42:43], v[146:147], v[20:21]
	v_fma_f32 v28, v28, v36, v35
	v_pk_fma_f32 v[0:1], v[148:149], v[28:29], v[14:15] op_sel_hi:[1,0,1]
	v_pk_fma_f32 v[2:3], v[150:151], v[28:29], v[16:17] op_sel_hi:[1,0,1]
	v_pk_mul_f32 v[22:23], v[14:15], v[60:61]
	v_pk_mul_f32 v[24:25], v[148:149], v[60:61]
	v_pk_fma_f32 v[22:23], v[16:17], v[62:63], v[22:23]
	v_pk_fma_f32 v[24:25], v[150:151], v[62:63], v[24:25]
	v_add_f32_e32 v26, v22, v23
	v_add_f32_e32 v27, v24, v25
	s_nop 0
	v_add_f32_dpp v26, v26, v26 quad_perm:[1,0,3,2] row_mask:0xf bank_mask:0xf bound_ctrl:1
	v_add_f32_dpp v27, v27, v27 quad_perm:[1,0,3,2] row_mask:0xf bank_mask:0xf bound_ctrl:1
	v_pk_mul_f32 v[32:33], v[40:41], v[128:129]
	v_pk_fma_f32 v[32:33], v[42:43], v[130:131], v[32:33]
	v_add_f32_dpp v26, v26, v26 quad_perm:[2,3,0,1] row_mask:0xf bank_mask:0xf bound_ctrl:1
	v_add_f32_dpp v27, v27, v27 quad_perm:[2,3,0,1] row_mask:0xf bank_mask:0xf bound_ctrl:1
	v_add_f32_e32 v32, v32, v33
	ds_write_b32 v10, v32 offset:2048
	v_add_f32_dpp v26, v26, v26 row_half_mirror row_mask:0xf bank_mask:0xf bound_ctrl:1
	v_add_f32_dpp v27, v27, v27 row_half_mirror row_mask:0xf bank_mask:0xf bound_ctrl:1
	v_mul_f32_e32 v30, v5, v68
	v_pk_mul_f32 v[18:19], v[64:65], v[30:31] op_sel_hi:[1,0]
	v_add_f32_dpp v35, v26, v26 row_mirror row_mask:0xf bank_mask:0xf bound_ctrl:1
	v_add_f32_dpp v36, v27, v27 row_mirror row_mask:0xf bank_mask:0xf bound_ctrl:1
	v_pk_mul_f32 v[20:21], v[66:67], v[30:31] op_sel_hi:[1,0]
	s_waitcnt lgkmcnt(4)
	ds_read_b128 v[108:111], v11 offset:9728
	ds_read_b128 v[112:115], v11 offset:9472
	ds_read_b32 v116, v12 offset:10496
	ds_read_b128 v[120:123], v11 offset:9216
	ds_read_b128 v[124:127], v11 offset:9984
	ds_read_b128 v[128:131], v11 offset:10240
	v_pk_fma_f32 v[14:15], v[0:1], v[72:73], v[18:19]
	v_pk_fma_f32 v[16:17], v[2:3], v[74:75], v[20:21]
	v_fma_f32 v28, v28, v36, v35
	v_pk_fma_f32 v[40:41], v[76:77], v[28:29], v[14:15] op_sel_hi:[1,0,1]
	v_pk_fma_f32 v[42:43], v[78:79], v[28:29], v[16:17] op_sel_hi:[1,0,1]
	v_pk_mul_f32 v[22:23], v[14:15], v[84:85]
	v_pk_mul_f32 v[24:25], v[76:77], v[84:85]
	v_pk_fma_f32 v[22:23], v[16:17], v[86:87], v[22:23]
	v_pk_fma_f32 v[24:25], v[78:79], v[86:87], v[24:25]
	v_add_f32_e32 v26, v22, v23
	v_add_f32_e32 v27, v24, v25
	s_nop 0
	v_add_f32_dpp v26, v26, v26 quad_perm:[1,0,3,2] row_mask:0xf bank_mask:0xf bound_ctrl:1
	v_add_f32_dpp v27, v27, v27 quad_perm:[1,0,3,2] row_mask:0xf bank_mask:0xf bound_ctrl:1
	v_pk_mul_f32 v[32:33], v[0:1], v[152:153]
	v_pk_fma_f32 v[32:33], v[2:3], v[154:155], v[32:33]
	v_add_f32_dpp v26, v26, v26 quad_perm:[2,3,0,1] row_mask:0xf bank_mask:0xf bound_ctrl:1
	v_add_f32_dpp v27, v27, v27 quad_perm:[2,3,0,1] row_mask:0xf bank_mask:0xf bound_ctrl:1
	v_add_f32_e32 v32, v32, v33
	ds_write_b32 v10, v32 offset:3072
	v_add_f32_dpp v26, v26, v26 row_half_mirror row_mask:0xf bank_mask:0xf bound_ctrl:1
	v_add_f32_dpp v27, v27, v27 row_half_mirror row_mask:0xf bank_mask:0xf bound_ctrl:1
	v_mul_f32_e32 v30, v5, v92
	v_pk_mul_f32 v[18:19], v[88:89], v[30:31] op_sel_hi:[1,0]
	v_add_f32_dpp v35, v26, v26 row_mirror row_mask:0xf bank_mask:0xf bound_ctrl:1
	v_add_f32_dpp v36, v27, v27 row_mirror row_mask:0xf bank_mask:0xf bound_ctrl:1
	v_pk_mul_f32 v[20:21], v[90:91], v[30:31] op_sel_hi:[1,0]
	s_waitcnt lgkmcnt(4)
	ds_read_b128 v[132:135], v11 offset:11264
	ds_read_b128 v[136:139], v11 offset:11008
	ds_read_b32 v140, v12 offset:12032
	ds_read_b128 v[144:147], v11 offset:10752
	ds_read_b128 v[148:151], v11 offset:11520
	ds_read_b128 v[152:155], v11 offset:11776
	v_pk_fma_f32 v[14:15], v[40:41], v[96:97], v[18:19]
	v_pk_fma_f32 v[16:17], v[42:43], v[98:99], v[20:21]
	v_fma_f32 v28, v28, v36, v35
	v_pk_fma_f32 v[0:1], v[100:101], v[28:29], v[14:15] op_sel_hi:[1,0,1]
	v_pk_fma_f32 v[2:3], v[102:103], v[28:29], v[16:17] op_sel_hi:[1,0,1]
	v_pk_mul_f32 v[22:23], v[14:15], v[108:109]
	v_pk_mul_f32 v[24:25], v[100:101], v[108:109]
	v_pk_fma_f32 v[22:23], v[16:17], v[110:111], v[22:23]
	v_pk_fma_f32 v[24:25], v[102:103], v[110:111], v[24:25]
	v_add_f32_e32 v26, v22, v23
	v_add_f32_e32 v27, v24, v25
	s_nop 0
	v_add_f32_dpp v26, v26, v26 quad_perm:[1,0,3,2] row_mask:0xf bank_mask:0xf bound_ctrl:1
	v_add_f32_dpp v27, v27, v27 quad_perm:[1,0,3,2] row_mask:0xf bank_mask:0xf bound_ctrl:1
	v_pk_mul_f32 v[32:33], v[40:41], v[80:81]
	v_pk_fma_f32 v[32:33], v[42:43], v[82:83], v[32:33]
	v_add_f32_dpp v26, v26, v26 quad_perm:[2,3,0,1] row_mask:0xf bank_mask:0xf bound_ctrl:1
	v_add_f32_dpp v27, v27, v27 quad_perm:[2,3,0,1] row_mask:0xf bank_mask:0xf bound_ctrl:1
	v_add_f32_e32 v32, v32, v33
	ds_write_b32 v10, v32 offset:4096
	v_add_f32_dpp v26, v26, v26 row_half_mirror row_mask:0xf bank_mask:0xf bound_ctrl:1
	v_add_f32_dpp v27, v27, v27 row_half_mirror row_mask:0xf bank_mask:0xf bound_ctrl:1
	v_mul_f32_e32 v30, v5, v116
	v_pk_mul_f32 v[18:19], v[112:113], v[30:31] op_sel_hi:[1,0]
	v_add_f32_dpp v35, v26, v26 row_mirror row_mask:0xf bank_mask:0xf bound_ctrl:1
	v_add_f32_dpp v36, v27, v27 row_mirror row_mask:0xf bank_mask:0xf bound_ctrl:1
	v_pk_mul_f32 v[20:21], v[114:115], v[30:31] op_sel_hi:[1,0]
	s_waitcnt lgkmcnt(4)
	ds_read_b128 v[60:63], v11 offset:12800
	ds_read_b128 v[64:67], v11 offset:12544
	ds_read_b32 v68, v12 offset:13568
	ds_read_b128 v[72:75], v11 offset:12288
	ds_read_b128 v[76:79], v11 offset:13056
	ds_read_b128 v[80:83], v11 offset:13312
	v_pk_fma_f32 v[14:15], v[0:1], v[120:121], v[18:19]
	v_pk_fma_f32 v[16:17], v[2:3], v[122:123], v[20:21]
	v_fma_f32 v28, v28, v36, v35
	v_pk_fma_f32 v[40:41], v[124:125], v[28:29], v[14:15] op_sel_hi:[1,0,1]
	v_pk_fma_f32 v[42:43], v[126:127], v[28:29], v[16:17] op_sel_hi:[1,0,1]
	v_pk_mul_f32 v[22:23], v[14:15], v[132:133]
	v_pk_mul_f32 v[24:25], v[124:125], v[132:133]
	v_pk_fma_f32 v[22:23], v[16:17], v[134:135], v[22:23]
	v_pk_fma_f32 v[24:25], v[126:127], v[134:135], v[24:25]
	v_add_f32_e32 v26, v22, v23
	v_add_f32_e32 v27, v24, v25
	s_nop 0
	v_add_f32_dpp v26, v26, v26 quad_perm:[1,0,3,2] row_mask:0xf bank_mask:0xf bound_ctrl:1
	v_add_f32_dpp v27, v27, v27 quad_perm:[1,0,3,2] row_mask:0xf bank_mask:0xf bound_ctrl:1
	v_pk_mul_f32 v[32:33], v[0:1], v[104:105]
	v_pk_fma_f32 v[32:33], v[2:3], v[106:107], v[32:33]
	v_add_f32_dpp v26, v26, v26 quad_perm:[2,3,0,1] row_mask:0xf bank_mask:0xf bound_ctrl:1
	v_add_f32_dpp v27, v27, v27 quad_perm:[2,3,0,1] row_mask:0xf bank_mask:0xf bound_ctrl:1
	v_add_f32_e32 v32, v32, v33
	ds_write_b32 v10, v32 offset:5120
	v_add_f32_dpp v26, v26, v26 row_half_mirror row_mask:0xf bank_mask:0xf bound_ctrl:1
	v_add_f32_dpp v27, v27, v27 row_half_mirror row_mask:0xf bank_mask:0xf bound_ctrl:1
	v_mul_f32_e32 v30, v5, v140
	v_pk_mul_f32 v[18:19], v[136:137], v[30:31] op_sel_hi:[1,0]
	v_add_f32_dpp v35, v26, v26 row_mirror row_mask:0xf bank_mask:0xf bound_ctrl:1
	v_add_f32_dpp v36, v27, v27 row_mirror row_mask:0xf bank_mask:0xf bound_ctrl:1
	v_pk_mul_f32 v[20:21], v[138:139], v[30:31] op_sel_hi:[1,0]
	s_waitcnt lgkmcnt(4)
	ds_read_b128 v[84:87], v11 offset:14336
	ds_read_b128 v[88:91], v11 offset:14080
	ds_read_b32 v92, v12 offset:15104
	ds_read_b128 v[96:99], v11 offset:13824
	ds_read_b128 v[100:103], v11 offset:14592
	ds_read_b128 v[104:107], v11 offset:14848
	v_pk_fma_f32 v[14:15], v[40:41], v[144:145], v[18:19]
	v_pk_fma_f32 v[16:17], v[42:43], v[146:147], v[20:21]
	v_fma_f32 v28, v28, v36, v35
	v_pk_fma_f32 v[0:1], v[148:149], v[28:29], v[14:15] op_sel_hi:[1,0,1]
	v_pk_fma_f32 v[2:3], v[150:151], v[28:29], v[16:17] op_sel_hi:[1,0,1]
	v_pk_mul_f32 v[22:23], v[14:15], v[60:61]
	v_pk_mul_f32 v[24:25], v[148:149], v[60:61]
	v_pk_fma_f32 v[22:23], v[16:17], v[62:63], v[22:23]
	v_pk_fma_f32 v[24:25], v[150:151], v[62:63], v[24:25]
	v_add_f32_e32 v26, v22, v23
	v_add_f32_e32 v27, v24, v25
	s_nop 0
	v_add_f32_dpp v26, v26, v26 quad_perm:[1,0,3,2] row_mask:0xf bank_mask:0xf bound_ctrl:1
	v_add_f32_dpp v27, v27, v27 quad_perm:[1,0,3,2] row_mask:0xf bank_mask:0xf bound_ctrl:1
	v_pk_mul_f32 v[32:33], v[40:41], v[128:129]
	v_pk_fma_f32 v[32:33], v[42:43], v[130:131], v[32:33]
	v_add_f32_dpp v26, v26, v26 quad_perm:[2,3,0,1] row_mask:0xf bank_mask:0xf bound_ctrl:1
	v_add_f32_dpp v27, v27, v27 quad_perm:[2,3,0,1] row_mask:0xf bank_mask:0xf bound_ctrl:1
	v_add_f32_e32 v32, v32, v33
	ds_write_b32 v10, v32 offset:6144
	v_add_f32_dpp v26, v26, v26 row_half_mirror row_mask:0xf bank_mask:0xf bound_ctrl:1
	v_add_f32_dpp v27, v27, v27 row_half_mirror row_mask:0xf bank_mask:0xf bound_ctrl:1
	v_mul_f32_e32 v30, v5, v68
	v_pk_mul_f32 v[18:19], v[64:65], v[30:31] op_sel_hi:[1,0]
	v_add_f32_dpp v35, v26, v26 row_mirror row_mask:0xf bank_mask:0xf bound_ctrl:1
	v_add_f32_dpp v36, v27, v27 row_mirror row_mask:0xf bank_mask:0xf bound_ctrl:1
	v_pk_mul_f32 v[20:21], v[66:67], v[30:31] op_sel_hi:[1,0]
	s_waitcnt lgkmcnt(4)
	ds_read_b128 v[108:111], v11 offset:15872
	ds_read_b128 v[112:115], v11 offset:15616
	ds_read_b32 v116, v12 offset:16640
	ds_read_b128 v[120:123], v11 offset:15360
	ds_read_b128 v[124:127], v11 offset:16128
	ds_read_b128 v[128:131], v11 offset:16384
	v_pk_fma_f32 v[14:15], v[0:1], v[72:73], v[18:19]
	v_pk_fma_f32 v[16:17], v[2:3], v[74:75], v[20:21]
	v_fma_f32 v28, v28, v36, v35
	v_pk_fma_f32 v[40:41], v[76:77], v[28:29], v[14:15] op_sel_hi:[1,0,1]
	v_pk_fma_f32 v[42:43], v[78:79], v[28:29], v[16:17] op_sel_hi:[1,0,1]
	v_pk_mul_f32 v[22:23], v[14:15], v[84:85]
	v_pk_mul_f32 v[24:25], v[76:77], v[84:85]
	v_pk_fma_f32 v[22:23], v[16:17], v[86:87], v[22:23]
	v_pk_fma_f32 v[24:25], v[78:79], v[86:87], v[24:25]
	v_add_f32_e32 v26, v22, v23
	v_add_f32_e32 v27, v24, v25
	s_nop 0
	v_add_f32_dpp v26, v26, v26 quad_perm:[1,0,3,2] row_mask:0xf bank_mask:0xf bound_ctrl:1
	v_add_f32_dpp v27, v27, v27 quad_perm:[1,0,3,2] row_mask:0xf bank_mask:0xf bound_ctrl:1
	v_pk_mul_f32 v[32:33], v[0:1], v[152:153]
	v_pk_fma_f32 v[32:33], v[2:3], v[154:155], v[32:33]
	v_add_f32_dpp v26, v26, v26 quad_perm:[2,3,0,1] row_mask:0xf bank_mask:0xf bound_ctrl:1
	v_add_f32_dpp v27, v27, v27 quad_perm:[2,3,0,1] row_mask:0xf bank_mask:0xf bound_ctrl:1
	v_add_f32_e32 v32, v32, v33
	ds_write_b32 v10, v32 offset:7168
	v_add_f32_dpp v26, v26, v26 row_half_mirror row_mask:0xf bank_mask:0xf bound_ctrl:1
	v_add_f32_dpp v27, v27, v27 row_half_mirror row_mask:0xf bank_mask:0xf bound_ctrl:1
	v_mul_f32_e32 v30, v5, v92
	v_pk_mul_f32 v[18:19], v[88:89], v[30:31] op_sel_hi:[1,0]
	v_add_f32_dpp v35, v26, v26 row_mirror row_mask:0xf bank_mask:0xf bound_ctrl:1
	v_add_f32_dpp v36, v27, v27 row_mirror row_mask:0xf bank_mask:0xf bound_ctrl:1
	v_pk_mul_f32 v[20:21], v[90:91], v[30:31] op_sel_hi:[1,0]
	s_waitcnt lgkmcnt(4)
	ds_read_b128 v[132:135], v11 offset:17408
	ds_read_b128 v[136:139], v11 offset:17152
	ds_read_b32 v140, v12 offset:18176
	ds_read_b128 v[144:147], v11 offset:16896
	ds_read_b128 v[148:151], v11 offset:17664
	ds_read_b128 v[152:155], v11 offset:17920
	v_pk_fma_f32 v[14:15], v[40:41], v[96:97], v[18:19]
	v_pk_fma_f32 v[16:17], v[42:43], v[98:99], v[20:21]
	v_fma_f32 v28, v28, v36, v35
	v_pk_fma_f32 v[0:1], v[100:101], v[28:29], v[14:15] op_sel_hi:[1,0,1]
	v_pk_fma_f32 v[2:3], v[102:103], v[28:29], v[16:17] op_sel_hi:[1,0,1]
	v_pk_mul_f32 v[22:23], v[14:15], v[108:109]
	v_pk_mul_f32 v[24:25], v[100:101], v[108:109]
	v_pk_fma_f32 v[22:23], v[16:17], v[110:111], v[22:23]
	v_pk_fma_f32 v[24:25], v[102:103], v[110:111], v[24:25]
	v_add_f32_e32 v26, v22, v23
	v_add_f32_e32 v27, v24, v25
	s_nop 0
	v_add_f32_dpp v26, v26, v26 quad_perm:[1,0,3,2] row_mask:0xf bank_mask:0xf bound_ctrl:1
	v_add_f32_dpp v27, v27, v27 quad_perm:[1,0,3,2] row_mask:0xf bank_mask:0xf bound_ctrl:1
	v_pk_mul_f32 v[32:33], v[40:41], v[80:81]
	v_pk_fma_f32 v[32:33], v[42:43], v[82:83], v[32:33]
	v_add_f32_dpp v26, v26, v26 quad_perm:[2,3,0,1] row_mask:0xf bank_mask:0xf bound_ctrl:1
	v_add_f32_dpp v27, v27, v27 quad_perm:[2,3,0,1] row_mask:0xf bank_mask:0xf bound_ctrl:1
	v_add_f32_e32 v32, v32, v33
	ds_write_b32 v10, v32 offset:8192
	v_add_f32_dpp v26, v26, v26 row_half_mirror row_mask:0xf bank_mask:0xf bound_ctrl:1
	v_add_f32_dpp v27, v27, v27 row_half_mirror row_mask:0xf bank_mask:0xf bound_ctrl:1
	v_mul_f32_e32 v30, v5, v116
	v_pk_mul_f32 v[18:19], v[112:113], v[30:31] op_sel_hi:[1,0]
	v_add_f32_dpp v35, v26, v26 row_mirror row_mask:0xf bank_mask:0xf bound_ctrl:1
	v_add_f32_dpp v36, v27, v27 row_mirror row_mask:0xf bank_mask:0xf bound_ctrl:1
	v_pk_mul_f32 v[20:21], v[114:115], v[30:31] op_sel_hi:[1,0]
	s_waitcnt lgkmcnt(4)
	ds_read_b128 v[60:63], v11 offset:18944
	ds_read_b128 v[64:67], v11 offset:18688
	ds_read_b32 v68, v12 offset:19712
	ds_read_b128 v[72:75], v11 offset:18432
	ds_read_b128 v[76:79], v11 offset:19200
	ds_read_b128 v[80:83], v11 offset:19456
	v_pk_fma_f32 v[14:15], v[0:1], v[120:121], v[18:19]
	v_pk_fma_f32 v[16:17], v[2:3], v[122:123], v[20:21]
	v_fma_f32 v28, v28, v36, v35
	v_pk_fma_f32 v[40:41], v[124:125], v[28:29], v[14:15] op_sel_hi:[1,0,1]
	v_pk_fma_f32 v[42:43], v[126:127], v[28:29], v[16:17] op_sel_hi:[1,0,1]
	v_pk_mul_f32 v[22:23], v[14:15], v[132:133]
	v_pk_mul_f32 v[24:25], v[124:125], v[132:133]
	v_pk_fma_f32 v[22:23], v[16:17], v[134:135], v[22:23]
	v_pk_fma_f32 v[24:25], v[126:127], v[134:135], v[24:25]
	v_add_f32_e32 v26, v22, v23
	v_add_f32_e32 v27, v24, v25
	s_nop 0
	v_add_f32_dpp v26, v26, v26 quad_perm:[1,0,3,2] row_mask:0xf bank_mask:0xf bound_ctrl:1
	v_add_f32_dpp v27, v27, v27 quad_perm:[1,0,3,2] row_mask:0xf bank_mask:0xf bound_ctrl:1
	v_pk_mul_f32 v[32:33], v[0:1], v[104:105]
	v_pk_fma_f32 v[32:33], v[2:3], v[106:107], v[32:33]
	v_add_f32_dpp v26, v26, v26 quad_perm:[2,3,0,1] row_mask:0xf bank_mask:0xf bound_ctrl:1
	v_add_f32_dpp v27, v27, v27 quad_perm:[2,3,0,1] row_mask:0xf bank_mask:0xf bound_ctrl:1
	v_add_f32_e32 v32, v32, v33
	ds_write_b32 v10, v32 offset:9216
	v_add_f32_dpp v26, v26, v26 row_half_mirror row_mask:0xf bank_mask:0xf bound_ctrl:1
	v_add_f32_dpp v27, v27, v27 row_half_mirror row_mask:0xf bank_mask:0xf bound_ctrl:1
	v_mul_f32_e32 v30, v5, v140
	v_pk_mul_f32 v[18:19], v[136:137], v[30:31] op_sel_hi:[1,0]
	v_add_f32_dpp v35, v26, v26 row_mirror row_mask:0xf bank_mask:0xf bound_ctrl:1
	v_add_f32_dpp v36, v27, v27 row_mirror row_mask:0xf bank_mask:0xf bound_ctrl:1
	v_pk_mul_f32 v[20:21], v[138:139], v[30:31] op_sel_hi:[1,0]
	s_waitcnt lgkmcnt(4)
	ds_read_b128 v[84:87], v11 offset:20480
	ds_read_b128 v[88:91], v11 offset:20224
	ds_read_b32 v92, v12 offset:21248
	ds_read_b128 v[96:99], v11 offset:19968
	ds_read_b128 v[100:103], v11 offset:20736
	ds_read_b128 v[104:107], v11 offset:20992
	v_pk_fma_f32 v[14:15], v[40:41], v[144:145], v[18:19]
	v_pk_fma_f32 v[16:17], v[42:43], v[146:147], v[20:21]
	v_fma_f32 v28, v28, v36, v35
	v_pk_fma_f32 v[0:1], v[148:149], v[28:29], v[14:15] op_sel_hi:[1,0,1]
	v_pk_fma_f32 v[2:3], v[150:151], v[28:29], v[16:17] op_sel_hi:[1,0,1]
	v_pk_mul_f32 v[22:23], v[14:15], v[60:61]
	v_pk_mul_f32 v[24:25], v[148:149], v[60:61]
	v_pk_fma_f32 v[22:23], v[16:17], v[62:63], v[22:23]
	v_pk_fma_f32 v[24:25], v[150:151], v[62:63], v[24:25]
	v_add_f32_e32 v26, v22, v23
	v_add_f32_e32 v27, v24, v25
	s_nop 0
	v_add_f32_dpp v26, v26, v26 quad_perm:[1,0,3,2] row_mask:0xf bank_mask:0xf bound_ctrl:1
	v_add_f32_dpp v27, v27, v27 quad_perm:[1,0,3,2] row_mask:0xf bank_mask:0xf bound_ctrl:1
	v_pk_mul_f32 v[32:33], v[40:41], v[128:129]
	v_pk_fma_f32 v[32:33], v[42:43], v[130:131], v[32:33]
	v_add_f32_dpp v26, v26, v26 quad_perm:[2,3,0,1] row_mask:0xf bank_mask:0xf bound_ctrl:1
	v_add_f32_dpp v27, v27, v27 quad_perm:[2,3,0,1] row_mask:0xf bank_mask:0xf bound_ctrl:1
	v_add_f32_e32 v32, v32, v33
	ds_write_b32 v10, v32 offset:10240
	v_add_f32_dpp v26, v26, v26 row_half_mirror row_mask:0xf bank_mask:0xf bound_ctrl:1
	v_add_f32_dpp v27, v27, v27 row_half_mirror row_mask:0xf bank_mask:0xf bound_ctrl:1
	v_mul_f32_e32 v30, v5, v68
	v_pk_mul_f32 v[18:19], v[64:65], v[30:31] op_sel_hi:[1,0]
	v_add_f32_dpp v35, v26, v26 row_mirror row_mask:0xf bank_mask:0xf bound_ctrl:1
	v_add_f32_dpp v36, v27, v27 row_mirror row_mask:0xf bank_mask:0xf bound_ctrl:1
	v_pk_mul_f32 v[20:21], v[66:67], v[30:31] op_sel_hi:[1,0]
	s_waitcnt lgkmcnt(4)
	ds_read_b128 v[108:111], v11 offset:22016
	ds_read_b128 v[112:115], v11 offset:21760
	ds_read_b32 v116, v12 offset:22784
	ds_read_b128 v[120:123], v11 offset:21504
	ds_read_b128 v[124:127], v11 offset:22272
	ds_read_b128 v[128:131], v11 offset:22528
	v_pk_fma_f32 v[14:15], v[0:1], v[72:73], v[18:19]
	v_pk_fma_f32 v[16:17], v[2:3], v[74:75], v[20:21]
	v_fma_f32 v28, v28, v36, v35
	v_pk_fma_f32 v[40:41], v[76:77], v[28:29], v[14:15] op_sel_hi:[1,0,1]
	v_pk_fma_f32 v[42:43], v[78:79], v[28:29], v[16:17] op_sel_hi:[1,0,1]
	v_pk_mul_f32 v[22:23], v[14:15], v[84:85]
	v_pk_mul_f32 v[24:25], v[76:77], v[84:85]
	v_pk_fma_f32 v[22:23], v[16:17], v[86:87], v[22:23]
	v_pk_fma_f32 v[24:25], v[78:79], v[86:87], v[24:25]
	v_add_f32_e32 v26, v22, v23
	v_add_f32_e32 v27, v24, v25
	s_nop 0
	v_add_f32_dpp v26, v26, v26 quad_perm:[1,0,3,2] row_mask:0xf bank_mask:0xf bound_ctrl:1
	v_add_f32_dpp v27, v27, v27 quad_perm:[1,0,3,2] row_mask:0xf bank_mask:0xf bound_ctrl:1
	v_pk_mul_f32 v[32:33], v[0:1], v[152:153]
	v_pk_fma_f32 v[32:33], v[2:3], v[154:155], v[32:33]
	v_add_f32_dpp v26, v26, v26 quad_perm:[2,3,0,1] row_mask:0xf bank_mask:0xf bound_ctrl:1
	v_add_f32_dpp v27, v27, v27 quad_perm:[2,3,0,1] row_mask:0xf bank_mask:0xf bound_ctrl:1
	v_add_f32_e32 v32, v32, v33
	ds_write_b32 v10, v32 offset:11264
	v_add_f32_dpp v26, v26, v26 row_half_mirror row_mask:0xf bank_mask:0xf bound_ctrl:1
	v_add_f32_dpp v27, v27, v27 row_half_mirror row_mask:0xf bank_mask:0xf bound_ctrl:1
	v_mul_f32_e32 v30, v5, v92
	v_pk_mul_f32 v[18:19], v[88:89], v[30:31] op_sel_hi:[1,0]
	v_add_f32_dpp v35, v26, v26 row_mirror row_mask:0xf bank_mask:0xf bound_ctrl:1
	v_add_f32_dpp v36, v27, v27 row_mirror row_mask:0xf bank_mask:0xf bound_ctrl:1
	v_pk_mul_f32 v[20:21], v[90:91], v[30:31] op_sel_hi:[1,0]
	s_waitcnt lgkmcnt(4)
	ds_read_b128 v[132:135], v11 offset:23552
	ds_read_b128 v[136:139], v11 offset:23296
	ds_read_b32 v140, v12 offset:24320
	ds_read_b128 v[144:147], v11 offset:23040
	ds_read_b128 v[148:151], v11 offset:23808
	ds_read_b128 v[152:155], v11 offset:24064
	v_pk_fma_f32 v[14:15], v[40:41], v[96:97], v[18:19]
	v_pk_fma_f32 v[16:17], v[42:43], v[98:99], v[20:21]
	v_fma_f32 v28, v28, v36, v35
	v_pk_fma_f32 v[0:1], v[100:101], v[28:29], v[14:15] op_sel_hi:[1,0,1]
	v_pk_fma_f32 v[2:3], v[102:103], v[28:29], v[16:17] op_sel_hi:[1,0,1]
	v_pk_mul_f32 v[22:23], v[14:15], v[108:109]
	v_pk_mul_f32 v[24:25], v[100:101], v[108:109]
	v_pk_fma_f32 v[22:23], v[16:17], v[110:111], v[22:23]
	v_pk_fma_f32 v[24:25], v[102:103], v[110:111], v[24:25]
	v_add_f32_e32 v26, v22, v23
	v_add_f32_e32 v27, v24, v25
	s_nop 0
	v_add_f32_dpp v26, v26, v26 quad_perm:[1,0,3,2] row_mask:0xf bank_mask:0xf bound_ctrl:1
	v_add_f32_dpp v27, v27, v27 quad_perm:[1,0,3,2] row_mask:0xf bank_mask:0xf bound_ctrl:1
	v_pk_mul_f32 v[32:33], v[40:41], v[80:81]
	v_pk_fma_f32 v[32:33], v[42:43], v[82:83], v[32:33]
	v_add_f32_dpp v26, v26, v26 quad_perm:[2,3,0,1] row_mask:0xf bank_mask:0xf bound_ctrl:1
	v_add_f32_dpp v27, v27, v27 quad_perm:[2,3,0,1] row_mask:0xf bank_mask:0xf bound_ctrl:1
	v_add_f32_e32 v32, v32, v33
	ds_write_b32 v10, v32 offset:12288
	v_add_f32_dpp v26, v26, v26 row_half_mirror row_mask:0xf bank_mask:0xf bound_ctrl:1
	v_add_f32_dpp v27, v27, v27 row_half_mirror row_mask:0xf bank_mask:0xf bound_ctrl:1
	v_mul_f32_e32 v30, v5, v116
	v_pk_mul_f32 v[18:19], v[112:113], v[30:31] op_sel_hi:[1,0]
	v_add_f32_dpp v35, v26, v26 row_mirror row_mask:0xf bank_mask:0xf bound_ctrl:1
	v_add_f32_dpp v36, v27, v27 row_mirror row_mask:0xf bank_mask:0xf bound_ctrl:1
	v_pk_mul_f32 v[20:21], v[114:115], v[30:31] op_sel_hi:[1,0]
	s_waitcnt lgkmcnt(4)
	v_pk_fma_f32 v[14:15], v[0:1], v[120:121], v[18:19]
	v_pk_fma_f32 v[16:17], v[2:3], v[122:123], v[20:21]
	v_fma_f32 v28, v28, v36, v35
	v_pk_fma_f32 v[40:41], v[124:125], v[28:29], v[14:15] op_sel_hi:[1,0,1]
	v_pk_fma_f32 v[42:43], v[126:127], v[28:29], v[16:17] op_sel_hi:[1,0,1]
	v_pk_mul_f32 v[22:23], v[14:15], v[132:133]
	v_pk_mul_f32 v[24:25], v[124:125], v[132:133]
	v_pk_fma_f32 v[22:23], v[16:17], v[134:135], v[22:23]
	v_pk_fma_f32 v[24:25], v[126:127], v[134:135], v[24:25]
	v_add_f32_e32 v26, v22, v23
	v_add_f32_e32 v27, v24, v25
	s_nop 0
	v_add_f32_dpp v26, v26, v26 quad_perm:[1,0,3,2] row_mask:0xf bank_mask:0xf bound_ctrl:1
	v_add_f32_dpp v27, v27, v27 quad_perm:[1,0,3,2] row_mask:0xf bank_mask:0xf bound_ctrl:1
	v_pk_mul_f32 v[32:33], v[0:1], v[104:105]
	v_pk_fma_f32 v[32:33], v[2:3], v[106:107], v[32:33]
	v_add_f32_dpp v26, v26, v26 quad_perm:[2,3,0,1] row_mask:0xf bank_mask:0xf bound_ctrl:1
	v_add_f32_dpp v27, v27, v27 quad_perm:[2,3,0,1] row_mask:0xf bank_mask:0xf bound_ctrl:1
	v_add_f32_e32 v32, v32, v33
	ds_write_b32 v10, v32 offset:13312
	v_add_f32_dpp v26, v26, v26 row_half_mirror row_mask:0xf bank_mask:0xf bound_ctrl:1
	v_add_f32_dpp v27, v27, v27 row_half_mirror row_mask:0xf bank_mask:0xf bound_ctrl:1
	v_mul_f32_e32 v30, v5, v140
	v_pk_mul_f32 v[18:19], v[136:137], v[30:31] op_sel_hi:[1,0]
	v_add_f32_dpp v35, v26, v26 row_mirror row_mask:0xf bank_mask:0xf bound_ctrl:1
	v_add_f32_dpp v36, v27, v27 row_mirror row_mask:0xf bank_mask:0xf bound_ctrl:1
	v_pk_mul_f32 v[20:21], v[138:139], v[30:31] op_sel_hi:[1,0]
	s_waitcnt lgkmcnt(0)
	v_pk_fma_f32 v[14:15], v[40:41], v[144:145], v[18:19]
	v_pk_fma_f32 v[16:17], v[42:43], v[146:147], v[20:21]
	v_fma_f32 v28, v28, v36, v35
	v_pk_fma_f32 v[0:1], v[148:149], v[28:29], v[14:15] op_sel_hi:[1,0,1]
	v_pk_fma_f32 v[2:3], v[150:151], v[28:29], v[16:17] op_sel_hi:[1,0,1]
	v_pk_mul_f32 v[32:33], v[40:41], v[128:129]
	v_pk_fma_f32 v[32:33], v[42:43], v[130:131], v[32:33]
	v_add_f32_e32 v32, v32, v33
	ds_write_b32 v10, v32 offset:14336
	v_mul_f32_e32 v33, v155, v3
	v_fmac_f32_e32 v33, v2, v154
	v_fmac_f32_e32 v33, v1, v153
	v_fmac_f32_e32 v33, v0, v152
	ds_write_b32 v10, v33 offset:15360
	s_add_i32 s11, s7, 1
	s_cmp_lg_u32 s7, 3
	s_cselect_b32 s7, s11, 0
	s_waitcnt lgkmcnt(0)
	s_addk_i32 s6, 0x1000
	s_cmp_eq_u32 s6, 0x80000
	s_barrier
	s_cbranch_scc0 .LBB0_892
	s_load_dwordx2 s[6:7], s[0:1], 0x150
	s_and_b64 s[12:13], s[4:5], exec
	s_mov_b32 s11, 0x2ee01800
	s_cselect_b32 s11, s11, 0x2ed81800
	v_ashrrev_i32_e32 v5, 31, v4
	s_waitcnt lgkmcnt(0)
	s_add_u32 s11, s6, s11
	s_addc_u32 s12, s7, 0
	s_lshl_b32 s6, s9, 2
	s_add_i32 s6, s6, s10
	s_ashr_i32 s7, s6, 31
	s_lshl_b64 s[6:7], s[6:7], 14
	s_add_u32 s6, s11, s6
	s_addc_u32 s7, s12, s7
	v_lshlrev_b64 v[4:5], 8, v[4:5]
	v_lshl_add_u64 v[4:5], s[6:7], 0, v[4:5]
	v_lshlrev_b32_e32 v168, 2, v7
	v_lshl_add_u64 v[4:5], v[4:5], 0, v[168:169]
	s_mov_b64 s[6:7], 0
	global_store_dwordx4 v[4:5], v[0:3], off
